# MLA attention: last next-tile LDS store issued before the final two PV MFMAs so its latency is covered ahead of the per-iteration barrier
# baseline (speedup 1.0000x reference)
; DI unsigned pack2(float a, float b) { f32x2 v = {a, b}; hwbf16x2 r = __builtin_convertvector(v, hwbf16x2); return __builtin_bit_cast(unsigned, r); }
; DI float fast_exp2(float x) { return __builtin_amdgcn_exp2f(x); }
; #define MLA_STORE(bufp) do { _Pragma("unroll") for (int i = 0; i < 3; ++i) *(LAS u32x4*)((bufp) + klds[i]) = kreg[i]; \
;                              _Pragma("unroll") for (int i = 0; i < 2; ++i) { LAS u32x2* dp = (LAS u32x2*)((bufp) + vlds[i]); \
;                                  dp[0] = (u32x2){vreg[i][0], vreg[i][1]}; dp[2] = (u32x2){vreg[i][2], vreg[i][3]}; } } while (0)
; template <int NDB>
; DI void softmax_only(f32x16& sacc, float& m, float& l, f32x16 (&oacc)[NDB], bf16x8 (&pf)[2]) {
;     ...
;     float pv[16], ls = 0.f;
; #pragma unroll
;     for (int i = 0; i < 16; ++i) { pv[i] = fast_exp2(sacc[i]); ls += pv[i]; }
;     l += ls;
; #pragma unroll
;     for (int s2 = 0; s2 < 2; ++s2) {
;         u32x4 pw;
; #pragma unroll
;         for (int q = 0; q < 4; ++q) pw[q] = pack2(pv[8 * s2 + 2 * q], pv[8 * s2 + 2 * q + 1]);
;         pf[s2] = __builtin_bit_cast(bf16x8, pw);
;     }
; DI void mla_attn_phase(const Params& p, LAS unsigned char* lds) {
;     ...
;                 bf16x8 vf[2][4], pf[2];
;                 load_vfrags<4, VSTR>(vf, kb + KBUF + r * VSTR + blk * 64 + h * 16);
;                 softmax_only<4>(sacc, m, l, oacc, pf);
; #pragma unroll
;                 for (int s2 = 0; s2 < 2; ++s2)
; #pragma unroll
;                     for (int db = 0; db < 4; ++db) oacc[db] = __builtin_amdgcn_mfma_f32_32x32x16_bf16(vf[s2][db], pf[s2], oacc[db], 0, 0, 0);
;             }
;             if (t + 1 < NT) MLA_STORE(lds + ((t + 1) & 1) * BUF);
;             __syncthreads();
.LBB1_1684:
	v_exp_f32_e32 v64, v64
	v_exp_f32_e32 v65, v65
	v_exp_f32_e32 v66, v66
	v_exp_f32_e32 v67, v67
	v_exp_f32_e32 v68, v68
	v_exp_f32_e32 v69, v69
	v_exp_f32_e32 v70, v70
	v_exp_f32_e32 v71, v71
	v_add_f32_e32 v181, 0, v64
	v_add_f32_e32 v181, v181, v65
	v_add_f32_e32 v181, v66, v181
	v_add_f32_e32 v181, v67, v181
	v_cvt_pk_bf16_f32 v64, v64, v65
	v_cvt_pk_bf16_f32 v65, v66, v67
	v_cvt_pk_bf16_f32 v66, v68, v69
	v_cvt_pk_bf16_f32 v67, v70, v71
	v_add_f32_e32 v181, v68, v181
	v_exp_f32_e32 v72, v72
	s_waitcnt lgkmcnt(0)
	v_mfma_f32_32x32x16_bf16 v[48:63], v[176:179], v[64:67], v[48:63]
	v_exp_f32_e32 v73, v73
	v_exp_f32_e32 v74, v74
	v_exp_f32_e32 v75, v75
	v_exp_f32_e32 v76, v76
	v_exp_f32_e32 v77, v77
	v_exp_f32_e32 v78, v78
	v_exp_f32_e32 v79, v79
	v_mfma_f32_32x32x16_bf16 v[32:47], v[172:175], v[64:67], v[32:47]
	v_add_f32_e32 v181, v69, v181
	s_add_i32 s2, s2, 1
	v_add_f32_e32 v181, v70, v181
	v_add_f32_e32 v181, v71, v181
	s_bitcmp1_b32 s2, 0
	v_add_f32_e32 v181, v72, v181
	v_cvt_pk_bf16_f32 v68, v72, v73
	v_mfma_f32_32x32x16_bf16 v[16:31], v[168:171], v[64:67], v[16:31]
	v_cvt_pk_bf16_f32 v69, v74, v75
	v_cvt_pk_bf16_f32 v70, v76, v77
	v_cvt_pk_bf16_f32 v71, v78, v79
	s_cselect_b32 s3, 0xac00, 0
	v_add_f32_e32 v181, v73, v181
	s_add_i32 s3, s3, 0
	v_add_f32_e32 v181, v74, v181
	v_mfma_f32_32x32x16_bf16 v[0:15], v[164:167], v[64:67], v[0:15]
	v_add_u32_e32 v64, s3, v230
	v_add_f32_e32 v181, v75, v181
	s_waitcnt vmcnt(0)
	ds_write_b128 v64, v[156:159]
	v_add_u32_e32 v64, s3, v231
	v_add_f32_e32 v181, v76, v181
	ds_write_b128 v64, v[152:155]
	v_add_u32_e32 v64, s3, v232
	v_mfma_f32_32x32x16_bf16 v[48:63], v[92:95], v[68:71], v[48:63]
	v_add_f32_e32 v181, v77, v181
	ds_write_b128 v64, v[160:163]
	v_add_u32_e32 v64, s3, v212
	v_add_f32_e32 v181, v78, v181
	v_add_u32_e32 v64, 0x6000, v64
	v_add_f32_e32 v181, v79, v181
	ds_write2_b64 v64, v[148:149], v[150:151] offset0:128 offset1:130
	v_add_u32_e32 v64, s3, v214
	v_add_u32_e32 v64, 0x6000, v64
	ds_write2_b64 v64, v[144:145], v[146:147] offset0:128 offset1:130
	v_mfma_f32_32x32x16_bf16 v[32:47], v[80:83], v[68:71], v[32:47]
	s_mov_b64 s[4:5], 0x6000
	v_add_f32_e32 v242, v180, v181
	v_lshl_add_u64 v[222:223], v[222:223], 0, s[46:47]
	v_lshl_add_u64 v[224:225], v[224:225], 0, s[46:47]
	v_lshl_add_u64 v[226:227], v[226:227], 0, s[4:5]
	v_mfma_f32_32x32x16_bf16 v[16:31], v[84:87], v[68:71], v[16:31]
	s_cmp_eq_u32 s2, 63
	s_waitcnt lgkmcnt(0)
	s_barrier
	v_mfma_f32_32x32x16_bf16 v[0:15], v[88:91], v[68:71], v[0:15]
	s_cbranch_scc1 .LBB1_1689
